# in-proj (EpiHyIn) epilogue: packed channel-major outputs lane-transposed via ds_bpermute so 4 adjacent lanes store one channel's contiguous 32B
# speedup vs baseline: 1.0048x; 1.0048x over previous
; __device__ __forceinline__ float ss_rinv(u64 v) { return __builtin_amdgcn_rsqf((float)v * SS_INV + 1e-6f); }
;     __device__ __forceinline__ void operator()(const f32x4 (&acc)[2][2][4][2], const pg8::Unit& u, int wr, int wc, int fr, int fq) const {
;     ...
;         for (int ai = 0; ai < 2; ++ai)
; #pragma unroll
;             for (int m = 0; m < 4; ++m) {
;                 const int row0 = u.pm * 256 + ai * 128 + wr * 64 + m * 16;
;                 if (row0 >= MREAL) continue;
;                 const u64x2 s01 = *(const u64x2*)(rowss + row0 + 4 * fq), s23 = *(const u64x2*)(rowss + row0 + 4 * fq + 2);
;                 f32x4 ri; ri[0] = ss_rinv(s01[0]); ri[1] = ss_rinv(s01[1]); ri[2] = ss_rinv(s23[0]); ri[3] = ss_rinv(s23[1]);
;                 int s, p0, L; row_decode(row0, s, p0, L);
;                 const size_t so = seq_off_ch(s); const int LS = seq_LS(s);
.LBB0_1007:
	v_mbcnt_lo_u32_b32 v247, -1, 0
	v_mbcnt_hi_u32_b32 v247, -1, v247
	v_and_b32_e32 v244, 3, v247
	v_lshlrev_b32_e32 v244, 6, v244
	v_and_b32_e32 v245, 60, v247
	v_or_b32_e32 v244, v244, v245
	v_lshrrev_b32_e32 v245, 2, v247
	v_and_b32_e32 v246, 15, v247
	v_sub_u32_e32 v245, v245, v246
	v_and_b32_e32 v246, 3, v247
	v_lshrrev_b32_e32 v247, 4, v247
	v_sub_u32_e32 v246, v246, v247
	v_lshlrev_b32_e32 v246, 3, v246
	s_lshl_b32 s9, s16, 8
	s_add_i32 s16, s9, s41
	s_mov_b32 s17, 0
	v_lshl_add_u64 v[236:237], s[16:17], 3, v[144:145]
	global_load_dwordx4 v[166:169], v[236:237], off offset:16
	global_load_dwordx4 v[170:173], v[236:237], off
	global_load_dwordx4 v[174:177], v[236:237], off offset:144
	global_load_dwordx4 v[178:181], v[236:237], off offset:128
	global_load_dwordx4 v[182:185], v[236:237], off offset:272
	global_load_dwordx4 v[186:189], v[236:237], off offset:256
	global_load_dwordx4 v[190:193], v[236:237], off offset:400
	global_load_dwordx4 v[194:197], v[236:237], off offset:384
	global_load_dwordx4 v[198:201], v[236:237], off offset:1040
	global_load_dwordx4 v[216:219], v[236:237], off offset:1024
	global_load_dwordx4 v[220:223], v[236:237], off offset:1168
	global_load_dwordx4 v[224:227], v[236:237], off offset:1152
	global_load_dwordx4 v[228:231], v[236:237], off offset:1296
	global_load_dwordx4 v[232:235], v[236:237], off offset:1280
	global_load_dwordx4 v[146:149], v[236:237], off offset:1424
	global_load_dwordx4 v[236:239], v[236:237], off offset:1408
	s_waitcnt vmcnt(0)
	s_add_i32 s17, s16, 0xffff8000
	s_lshl_b32 s9, s18, 8
	s_lshr_b32 s23, s17, 12
	s_ashr_i32 s11, s18, 2
	s_and_b32 s9, s9, 0x300
	s_add_i32 s23, s23, 4
	s_ashr_i32 s22, s16, 13
	v_or_b32_e32 v164, s9, v162
	s_mul_hi_i32 s9, s11, 0xc300000
	s_mul_i32 s11, s11, 0xc300000
	s_cmp_gt_i32 s16, 0x1813f
	s_cbranch_scc1 .LBB0_1016
	s_ashr_i32 s17, s16, 31
	v_mov_b64_e32 v[130:131], v[166:167]
	v_mov_b64_e32 v[132:133], v[168:169]
	v_mov_b64_e32 v[134:135], v[170:171]
	v_mov_b64_e32 v[136:137], v[172:173]
	s_cmpk_gt_i32 s16, 0x7fff
	s_mov_b64 s[18:19], -1
	s_cbranch_scc0 .LBB0_1025
	s_cmp_gt_u32 s16, 0x17fff
	s_cbranch_scc0 .LBB0_1011
	s_add_i32 s17, s16, 0xfffe8000
	s_lshr_b32 s24, s17, 4
	s_mov_b64 s[18:19], 0

; __device__ __forceinline__ float ss_rinv(u64 v) { return __builtin_amdgcn_rsqf((float)v * SS_INV + 1e-6f); }
; __device__ __forceinline__ unsigned cvtpk(float lo, float hi) { f32x2 v = {lo, hi}; bf16x2_t b = __builtin_convertvector(v, bf16x2_t); return __builtin_bit_cast(unsigned, b); }
;     __device__ __forceinline__ void operator()(const f32x4 (&acc)[2][2][4][2], const pg8::Unit& u, int wr, int wc, int fr, int fq) const {
;     ...
;                 const u64x2 s01 = *(const u64x2*)(rowss + row0 + 4 * fq), s23 = *(const u64x2*)(rowss + row0 + 4 * fq + 2);
;                 f32x4 ri; ri[0] = ss_rinv(s01[0]); ri[1] = ss_rinv(s01[1]); ri[2] = ss_rinv(s23[0]); ri[3] = ss_rinv(s23[1]);
;                 int s, p0, L; row_decode(row0, s, p0, L);
;                 const size_t so = seq_off_ch(s); const int LS = seq_LS(s);
; #pragma unroll
;                 for (int bj = 0; bj < 2; ++bj)
; #pragma unroll
;                     for (int n = 0; n < 2; ++n) {
;                         const int col = u.pn * 256 + bj * 128 + wc * 32 + n * 16 + fr;
;                         const int part = col >> 10, ch = col & 1023;
;                         const f32x4 v = acc[ai][bj][m][n] * ri;
;                         u32x2 w; w.x = cvtpk(v[0], v[1]); w.y = cvtpk(v[2], v[3]);
;                         *(u32x2*)(XT + (size_t)part * REGION + so + (size_t)ch * LS + XPAD + p0 + 4 * fq) = w;
;                     }
.LBB0_1029:
	v_ffbh_u32_e32 v32, v135
	v_min_u32_e32 v32, 32, v32
	v_lshlrev_b64 v[134:135], v32, v[134:135]
	v_min_u32_e32 v134, 1, v134
	v_or_b32_e32 v134, v135, v134
	v_cvt_f32_u32_e32 v134, v134
	v_ffbh_u32_e32 v135, v137
	v_sub_u32_e32 v32, 32, v32
	v_min_u32_e32 v135, 32, v135
	v_ldexp_f32 v32, v134, v32
	v_fmamk_f32 v32, v32, 0x30800000, v203
	v_lshlrev_b64 v[136:137], v135, v[136:137]
	v_rsq_f32_e32 v134, v32
	v_min_u32_e32 v32, 1, v136
	v_ffbh_u32_e32 v136, v131
	v_min_u32_e32 v136, 32, v136
	v_lshlrev_b64 v[130:131], v136, v[130:131]
	v_min_u32_e32 v130, 1, v130
	v_or_b32_e32 v32, v137, v32
	v_or_b32_e32 v130, v131, v130
	v_cvt_f32_u32_e32 v32, v32
	v_cvt_f32_u32_e32 v130, v130
	v_sub_u32_e32 v135, 32, v135
	v_sub_u32_e32 v131, 32, v136
	v_ldexp_f32 v32, v32, v135
	v_ldexp_f32 v135, v130, v131
	v_ffbh_u32_e32 v130, v133
	v_min_u32_e32 v136, 32, v130
	v_lshlrev_b64 v[130:131], v136, v[132:133]
	v_min_u32_e32 v130, 1, v130
	v_or_b32_e32 v130, v131, v130
	v_cvt_f32_u32_e32 v131, v130
	v_sub_u32_e32 v132, 32, v136
	v_fmamk_f32 v32, v32, 0x30800000, v203
	v_fmamk_f32 v130, v135, 0x30800000, v203
	v_ldexp_f32 v131, v131, v132
	v_fmamk_f32 v131, v131, 0x30800000, v203
	v_rsq_f32_e32 v130, v130
	v_rsq_f32_e32 v131, v131
	v_rsq_f32_e32 v135, v32
	s_add_u32 s20, s39, s11
	s_addc_u32 s21, s40, s9
	s_lshl_b64 s[18:19], s[18:19], 1
	s_add_u32 s18, s20, s18
	v_mul_u32_u24_e32 v136, s17, v164
	v_mul_i32_i24_e32 v242, s17, v245
	v_lshl_add_u32 v242, v242, 1, v246
	v_ashrrev_i32_e32 v243, 31, v242
	v_pk_mul_f32 v[128:129], v[128:129], v[130:131]
	v_pk_mul_f32 v[126:127], v[126:127], v[134:135]
	s_addc_u32 s19, s21, s19
	v_lshlrev_b32_e32 v32, 1, v136
	v_cvt_pk_bf16_f32 v126, v126, v127
	v_cvt_pk_bf16_f32 v127, v128, v129
	v_lshl_add_u64 v[128:129], s[18:19], 0, v[32:33]
	s_lshl_b64 s[20:21], s[56:57], 1
	v_pk_mul_f32 v[124:125], v[124:125], v[130:131]
	v_pk_mul_f32 v[122:123], v[122:123], v[134:135]
	s_lshl_b32 s24, s17, 4
	s_lshl_b32 s56, s17, 5
	s_mulk_i32 s17, 0x70
	v_cvt_pk_bf16_f32 v122, v122, v123
	v_cvt_pk_bf16_f32 v123, v124, v125
	v_lshl_add_u64 v[124:125], v[128:129], 0, s[56:57]
	s_lshl_b32 s56, s17, 1
	s_add_i32 s17, s24, s17
	v_pk_mul_f32 v[116:117], v[116:117], v[130:131]
	v_pk_mul_f32 v[114:115], v[114:115], v[134:135]
	s_add_i32 s17, s17, s24
	v_lshl_add_u64 v[132:133], v[128:129], 0, s[20:21]
	v_lshlrev_b32_e32 v32, 1, v142
	v_pk_mul_f32 v[120:121], v[120:121], v[130:131]
	v_pk_mul_f32 v[118:119], v[118:119], v[134:135]
	v_cvt_pk_bf16_f32 v114, v114, v115
	v_cvt_pk_bf16_f32 v115, v116, v117
	v_add_lshl_u32 v116, s17, v136, 1
	v_mov_b32_e32 v117, v33
	v_lshl_add_u64 v[132:133], v[132:133], 0, v[32:33]
	v_cvt_pk_bf16_f32 v118, v118, v119
	v_cvt_pk_bf16_f32 v119, v120, v121
	v_lshl_add_u64 v[120:121], v[124:125], 0, s[56:57]
	v_lshl_add_u64 v[116:117], s[18:19], 0, v[116:117]
	ds_bpermute_b32 v126, v244, v126
	ds_bpermute_b32 v127, v244, v127
	ds_bpermute_b32 v122, v244, v122
	ds_bpermute_b32 v123, v244, v123
	ds_bpermute_b32 v118, v244, v118
	ds_bpermute_b32 v119, v244, v119
	ds_bpermute_b32 v114, v244, v114
	ds_bpermute_b32 v115, v244, v115
	v_lshl_add_u64 v[132:133], v[242:243], 0, v[132:133]
	s_waitcnt lgkmcnt(0)
	global_store_dwordx2 v[132:133], v[126:127], off offset:96
	v_lshl_add_u64 v[126:127], v[124:125], 0, s[20:21]
	v_lshl_add_u64 v[120:121], v[120:121], 0, s[20:21]
	v_lshl_add_u64 v[116:117], v[116:117], 0, s[20:21]
	v_lshl_add_u64 v[126:127], v[126:127], 0, v[32:33]
	v_lshl_add_u64 v[120:121], v[120:121], 0, v[32:33]
	v_lshl_add_u64 v[116:117], v[116:117], 0, v[32:33]
	v_lshl_add_u64 v[126:127], v[242:243], 0, v[126:127]
	global_store_dwordx2 v[126:127], v[122:123], off offset:96
	v_lshl_add_u64 v[120:121], v[242:243], 0, v[120:121]
	global_store_dwordx2 v[120:121], v[118:119], off offset:96
	v_lshl_add_u64 v[116:117], v[242:243], 0, v[116:117]
	global_store_dwordx2 v[116:117], v[114:115], off offset:96
	s_or_b32 s20, s16, 16
	s_cmp_gt_i32 s20, 0x1813f
	s_cbranch_scc0 .LBB0_1017

; __device__ __forceinline__ float ss_rinv(u64 v) { return __builtin_amdgcn_rsqf((float)v * SS_INV + 1e-6f); }
; __device__ __forceinline__ unsigned cvtpk(float lo, float hi) { f32x2 v = {lo, hi}; bf16x2_t b = __builtin_convertvector(v, bf16x2_t); return __builtin_bit_cast(unsigned, b); }
;     __device__ __forceinline__ void operator()(const f32x4 (&acc)[2][2][4][2], const pg8::Unit& u, int wr, int wc, int fr, int fq) const {
;     ...
;                 const u64x2 s01 = *(const u64x2*)(rowss + row0 + 4 * fq), s23 = *(const u64x2*)(rowss + row0 + 4 * fq + 2);
;                 f32x4 ri; ri[0] = ss_rinv(s01[0]); ri[1] = ss_rinv(s01[1]); ri[2] = ss_rinv(s23[0]); ri[3] = ss_rinv(s23[1]);
;                 int s, p0, L; row_decode(row0, s, p0, L);
;                 const size_t so = seq_off_ch(s); const int LS = seq_LS(s);
; #pragma unroll
;                 for (int bj = 0; bj < 2; ++bj)
; #pragma unroll
;                     for (int n = 0; n < 2; ++n) {
;                         const int col = u.pn * 256 + bj * 128 + wc * 32 + n * 16 + fr;
;                         const int part = col >> 10, ch = col & 1023;
;                         const f32x4 v = acc[ai][bj][m][n] * ri;
;                         u32x2 w; w.x = cvtpk(v[0], v[1]); w.y = cvtpk(v[2], v[3]);
;                         *(u32x2*)(XT + (size_t)part * REGION + so + (size_t)ch * LS + XPAD + p0 + 4 * fq) = w;
;                     }
.LBB0_1043:
	v_ffbh_u32_e32 v32, v119
	v_min_u32_e32 v32, 32, v32
	v_lshlrev_b64 v[118:119], v32, v[118:119]
	v_min_u32_e32 v118, 1, v118
	v_or_b32_e32 v118, v119, v118
	v_cvt_f32_u32_e32 v118, v118
	v_ffbh_u32_e32 v119, v121
	v_sub_u32_e32 v32, 32, v32
	v_min_u32_e32 v119, 32, v119
	v_ldexp_f32 v32, v118, v32
	v_fmamk_f32 v32, v32, 0x30800000, v203
	v_lshlrev_b64 v[120:121], v119, v[120:121]
	v_rsq_f32_e32 v118, v32
	v_min_u32_e32 v32, 1, v120
	v_ffbh_u32_e32 v120, v115
	v_min_u32_e32 v120, 32, v120
	v_lshlrev_b64 v[114:115], v120, v[114:115]
	v_min_u32_e32 v114, 1, v114
	v_or_b32_e32 v32, v121, v32
	v_or_b32_e32 v114, v115, v114
	v_cvt_f32_u32_e32 v32, v32
	v_cvt_f32_u32_e32 v114, v114
	v_sub_u32_e32 v119, 32, v119
	v_sub_u32_e32 v115, 32, v120
	v_ldexp_f32 v32, v32, v119
	v_ldexp_f32 v119, v114, v115
	v_ffbh_u32_e32 v114, v117
	v_min_u32_e32 v120, 32, v114
	v_lshlrev_b64 v[114:115], v120, v[116:117]
	v_min_u32_e32 v114, 1, v114
	v_or_b32_e32 v114, v115, v114
	v_cvt_f32_u32_e32 v115, v114
	v_sub_u32_e32 v116, 32, v120
	v_fmamk_f32 v32, v32, 0x30800000, v203
	v_fmamk_f32 v114, v119, 0x30800000, v203
	v_ldexp_f32 v115, v115, v116
	v_fmamk_f32 v115, v115, 0x30800000, v203
	v_rsq_f32_e32 v114, v114
	v_rsq_f32_e32 v115, v115
	v_rsq_f32_e32 v119, v32
	s_add_u32 s20, s39, s11
	s_addc_u32 s21, s40, s9
	s_lshl_b64 s[18:19], s[18:19], 1
	s_add_u32 s18, s20, s18
	v_mul_u32_u24_e32 v120, s17, v164
	v_mul_i32_i24_e32 v242, s17, v245
	v_lshl_add_u32 v242, v242, 1, v246
	v_ashrrev_i32_e32 v243, 31, v242
	v_pk_mul_f32 v[112:113], v[112:113], v[114:115]
	v_pk_mul_f32 v[110:111], v[110:111], v[118:119]
	s_addc_u32 s19, s21, s19
	v_lshlrev_b32_e32 v32, 1, v120
	v_cvt_pk_bf16_f32 v110, v110, v111
	v_cvt_pk_bf16_f32 v111, v112, v113
	v_lshl_add_u64 v[112:113], s[18:19], 0, v[32:33]
	s_lshl_b64 s[20:21], s[56:57], 1
	v_pk_mul_f32 v[108:109], v[108:109], v[114:115]
	v_pk_mul_f32 v[106:107], v[106:107], v[118:119]
	s_lshl_b32 s24, s17, 4
	s_lshl_b32 s56, s17, 5
	s_mulk_i32 s17, 0x70
	v_cvt_pk_bf16_f32 v106, v106, v107
	v_cvt_pk_bf16_f32 v107, v108, v109
	v_lshl_add_u64 v[108:109], v[112:113], 0, s[56:57]
	s_lshl_b32 s56, s17, 1
	s_add_i32 s17, s24, s17
	v_pk_mul_f32 v[100:101], v[100:101], v[114:115]
	v_pk_mul_f32 v[98:99], v[98:99], v[118:119]
	s_add_i32 s17, s17, s24
	v_lshl_add_u64 v[116:117], v[112:113], 0, s[20:21]
	v_lshlrev_b32_e32 v32, 1, v142
	v_pk_mul_f32 v[104:105], v[104:105], v[114:115]
	v_pk_mul_f32 v[102:103], v[102:103], v[118:119]
	v_cvt_pk_bf16_f32 v98, v98, v99
	v_cvt_pk_bf16_f32 v99, v100, v101
	v_add_lshl_u32 v100, s17, v120, 1
	v_mov_b32_e32 v101, v33
	v_lshl_add_u64 v[116:117], v[116:117], 0, v[32:33]
	v_cvt_pk_bf16_f32 v102, v102, v103
	v_cvt_pk_bf16_f32 v103, v104, v105
	v_lshl_add_u64 v[104:105], v[108:109], 0, s[56:57]
	v_lshl_add_u64 v[100:101], s[18:19], 0, v[100:101]
	ds_bpermute_b32 v110, v244, v110
	ds_bpermute_b32 v111, v244, v111
	ds_bpermute_b32 v106, v244, v106
	ds_bpermute_b32 v107, v244, v107
	ds_bpermute_b32 v102, v244, v102
	ds_bpermute_b32 v103, v244, v103
	ds_bpermute_b32 v98, v244, v98
	ds_bpermute_b32 v99, v244, v99
	v_lshl_add_u64 v[116:117], v[242:243], 0, v[116:117]
	s_waitcnt lgkmcnt(0)
	global_store_dwordx2 v[116:117], v[110:111], off offset:96
	v_lshl_add_u64 v[110:111], v[108:109], 0, s[20:21]
	v_lshl_add_u64 v[104:105], v[104:105], 0, s[20:21]
	v_lshl_add_u64 v[100:101], v[100:101], 0, s[20:21]
	v_lshl_add_u64 v[110:111], v[110:111], 0, v[32:33]
	v_lshl_add_u64 v[104:105], v[104:105], 0, v[32:33]
	v_lshl_add_u64 v[100:101], v[100:101], 0, v[32:33]
	v_lshl_add_u64 v[110:111], v[242:243], 0, v[110:111]
	global_store_dwordx2 v[110:111], v[106:107], off offset:96
	v_lshl_add_u64 v[104:105], v[242:243], 0, v[104:105]
	global_store_dwordx2 v[104:105], v[102:103], off offset:96
	v_lshl_add_u64 v[100:101], v[242:243], 0, v[100:101]
	global_store_dwordx2 v[100:101], v[98:99], off offset:96
	s_or_b32 s20, s16, 32
	s_cmp_gt_i32 s20, 0x1813f
	s_cbranch_scc0 .LBB0_1031

; __device__ __forceinline__ float ss_rinv(u64 v) { return __builtin_amdgcn_rsqf((float)v * SS_INV + 1e-6f); }
; __device__ __forceinline__ unsigned cvtpk(float lo, float hi) { f32x2 v = {lo, hi}; bf16x2_t b = __builtin_convertvector(v, bf16x2_t); return __builtin_bit_cast(unsigned, b); }
;     __device__ __forceinline__ void operator()(const f32x4 (&acc)[2][2][4][2], const pg8::Unit& u, int wr, int wc, int fr, int fq) const {
;     ...
;                 const u64x2 s01 = *(const u64x2*)(rowss + row0 + 4 * fq), s23 = *(const u64x2*)(rowss + row0 + 4 * fq + 2);
;                 f32x4 ri; ri[0] = ss_rinv(s01[0]); ri[1] = ss_rinv(s01[1]); ri[2] = ss_rinv(s23[0]); ri[3] = ss_rinv(s23[1]);
;                 int s, p0, L; row_decode(row0, s, p0, L);
;                 const size_t so = seq_off_ch(s); const int LS = seq_LS(s);
; #pragma unroll
;                 for (int bj = 0; bj < 2; ++bj)
; #pragma unroll
;                     for (int n = 0; n < 2; ++n) {
;                         const int col = u.pn * 256 + bj * 128 + wc * 32 + n * 16 + fr;
;                         const int part = col >> 10, ch = col & 1023;
;                         const f32x4 v = acc[ai][bj][m][n] * ri;
;                         u32x2 w; w.x = cvtpk(v[0], v[1]); w.y = cvtpk(v[2], v[3]);
;                         *(u32x2*)(XT + (size_t)part * REGION + so + (size_t)ch * LS + XPAD + p0 + 4 * fq) = w;
;                     }
.LBB0_1049:
	v_ffbh_u32_e32 v32, v103
	v_min_u32_e32 v32, 32, v32
	v_lshlrev_b64 v[102:103], v32, v[102:103]
	v_min_u32_e32 v102, 1, v102
	v_or_b32_e32 v102, v103, v102
	v_cvt_f32_u32_e32 v102, v102
	v_ffbh_u32_e32 v103, v105
	v_sub_u32_e32 v32, 32, v32
	v_min_u32_e32 v103, 32, v103
	v_ldexp_f32 v32, v102, v32
	v_fmamk_f32 v32, v32, 0x30800000, v203
	v_lshlrev_b64 v[104:105], v103, v[104:105]
	v_rsq_f32_e32 v102, v32
	v_min_u32_e32 v32, 1, v104
	v_ffbh_u32_e32 v104, v99
	v_min_u32_e32 v104, 32, v104
	v_lshlrev_b64 v[98:99], v104, v[98:99]
	v_min_u32_e32 v98, 1, v98
	v_or_b32_e32 v32, v105, v32
	v_or_b32_e32 v98, v99, v98
	v_cvt_f32_u32_e32 v32, v32
	v_cvt_f32_u32_e32 v98, v98
	v_sub_u32_e32 v103, 32, v103
	v_sub_u32_e32 v99, 32, v104
	v_ldexp_f32 v32, v32, v103
	v_ldexp_f32 v103, v98, v99
	v_ffbh_u32_e32 v98, v101
	v_min_u32_e32 v104, 32, v98
	v_lshlrev_b64 v[98:99], v104, v[100:101]
	v_min_u32_e32 v98, 1, v98
	v_or_b32_e32 v98, v99, v98
	v_cvt_f32_u32_e32 v99, v98
	v_sub_u32_e32 v100, 32, v104
	v_fmamk_f32 v32, v32, 0x30800000, v203
	v_fmamk_f32 v98, v103, 0x30800000, v203
	v_ldexp_f32 v99, v99, v100
	v_fmamk_f32 v99, v99, 0x30800000, v203
	v_rsq_f32_e32 v98, v98
	v_rsq_f32_e32 v99, v99
	v_rsq_f32_e32 v103, v32
	s_add_u32 s20, s39, s11
	s_addc_u32 s21, s40, s9
	s_lshl_b64 s[18:19], s[18:19], 1
	s_add_u32 s18, s20, s18
	v_mul_u32_u24_e32 v104, s17, v164
	v_mul_i32_i24_e32 v242, s17, v245
	v_lshl_add_u32 v242, v242, 1, v246
	v_ashrrev_i32_e32 v243, 31, v242
	v_pk_mul_f32 v[96:97], v[96:97], v[98:99]
	v_pk_mul_f32 v[94:95], v[94:95], v[102:103]
	s_addc_u32 s19, s21, s19
	v_lshlrev_b32_e32 v32, 1, v104
	v_cvt_pk_bf16_f32 v94, v94, v95
	v_cvt_pk_bf16_f32 v95, v96, v97
	v_lshl_add_u64 v[96:97], s[18:19], 0, v[32:33]
	s_lshl_b64 s[20:21], s[56:57], 1
	v_pk_mul_f32 v[92:93], v[92:93], v[98:99]
	v_pk_mul_f32 v[90:91], v[90:91], v[102:103]
	s_lshl_b32 s24, s17, 4
	s_lshl_b32 s56, s17, 5
	s_mulk_i32 s17, 0x70
	v_cvt_pk_bf16_f32 v90, v90, v91
	v_cvt_pk_bf16_f32 v91, v92, v93
	v_lshl_add_u64 v[92:93], v[96:97], 0, s[56:57]
	s_lshl_b32 s56, s17, 1
	s_add_i32 s17, s24, s17
	v_pk_mul_f32 v[84:85], v[84:85], v[98:99]
	v_pk_mul_f32 v[82:83], v[82:83], v[102:103]
	s_add_i32 s17, s17, s24
	v_lshl_add_u64 v[100:101], v[96:97], 0, s[20:21]
	v_lshlrev_b32_e32 v32, 1, v142
	v_pk_mul_f32 v[88:89], v[88:89], v[98:99]
	v_pk_mul_f32 v[86:87], v[86:87], v[102:103]
	v_cvt_pk_bf16_f32 v82, v82, v83
	v_cvt_pk_bf16_f32 v83, v84, v85
	v_add_lshl_u32 v84, s17, v104, 1
	v_mov_b32_e32 v85, v33
	v_lshl_add_u64 v[100:101], v[100:101], 0, v[32:33]
	v_cvt_pk_bf16_f32 v86, v86, v87
	v_cvt_pk_bf16_f32 v87, v88, v89
	v_lshl_add_u64 v[88:89], v[92:93], 0, s[56:57]
	v_lshl_add_u64 v[84:85], s[18:19], 0, v[84:85]
	ds_bpermute_b32 v94, v244, v94
	ds_bpermute_b32 v95, v244, v95
	ds_bpermute_b32 v90, v244, v90
	ds_bpermute_b32 v91, v244, v91
	ds_bpermute_b32 v86, v244, v86
	ds_bpermute_b32 v87, v244, v87
	ds_bpermute_b32 v82, v244, v82
	ds_bpermute_b32 v83, v244, v83
	v_lshl_add_u64 v[100:101], v[242:243], 0, v[100:101]
	s_waitcnt lgkmcnt(0)
	global_store_dwordx2 v[100:101], v[94:95], off offset:96
	v_lshl_add_u64 v[94:95], v[92:93], 0, s[20:21]
	v_lshl_add_u64 v[88:89], v[88:89], 0, s[20:21]
	v_lshl_add_u64 v[84:85], v[84:85], 0, s[20:21]
	v_lshl_add_u64 v[94:95], v[94:95], 0, v[32:33]
	v_lshl_add_u64 v[88:89], v[88:89], 0, v[32:33]
	v_lshl_add_u64 v[84:85], v[84:85], 0, v[32:33]
	v_lshl_add_u64 v[94:95], v[242:243], 0, v[94:95]
	global_store_dwordx2 v[94:95], v[90:91], off offset:96
	v_lshl_add_u64 v[88:89], v[242:243], 0, v[88:89]
	global_store_dwordx2 v[88:89], v[86:87], off offset:96
	v_lshl_add_u64 v[84:85], v[242:243], 0, v[84:85]
	global_store_dwordx2 v[84:85], v[82:83], off offset:96
	s_or_b32 s20, s16, 48
	s_cmp_gt_i32 s20, 0x1813f
	s_cbranch_scc1 .LBB0_1063

; __device__ __forceinline__ float ss_rinv(u64 v) { return __builtin_amdgcn_rsqf((float)v * SS_INV + 1e-6f); }
; __device__ __forceinline__ unsigned cvtpk(float lo, float hi) { f32x2 v = {lo, hi}; bf16x2_t b = __builtin_convertvector(v, bf16x2_t); return __builtin_bit_cast(unsigned, b); }
;     __device__ __forceinline__ void operator()(const f32x4 (&acc)[2][2][4][2], const pg8::Unit& u, int wr, int wc, int fr, int fq) const {
;     ...
;                 const u64x2 s01 = *(const u64x2*)(rowss + row0 + 4 * fq), s23 = *(const u64x2*)(rowss + row0 + 4 * fq + 2);
;                 f32x4 ri; ri[0] = ss_rinv(s01[0]); ri[1] = ss_rinv(s01[1]); ri[2] = ss_rinv(s23[0]); ri[3] = ss_rinv(s23[1]);
;                 int s, p0, L; row_decode(row0, s, p0, L);
;                 const size_t so = seq_off_ch(s); const int LS = seq_LS(s);
; #pragma unroll
;                 for (int bj = 0; bj < 2; ++bj)
; #pragma unroll
;                     for (int n = 0; n < 2; ++n) {
;                         const int col = u.pn * 256 + bj * 128 + wc * 32 + n * 16 + fr;
;                         const int part = col >> 10, ch = col & 1023;
;                         const f32x4 v = acc[ai][bj][m][n] * ri;
;                         u32x2 w; w.x = cvtpk(v[0], v[1]); w.y = cvtpk(v[2], v[3]);
;                         *(u32x2*)(XT + (size_t)part * REGION + so + (size_t)ch * LS + XPAD + p0 + 4 * fq) = w;
;                     }
.LBB0_1062:
	v_ffbh_u32_e32 v32, v87
	v_min_u32_e32 v32, 32, v32
	v_lshlrev_b64 v[86:87], v32, v[86:87]
	v_min_u32_e32 v86, 1, v86
	v_or_b32_e32 v86, v87, v86
	v_cvt_f32_u32_e32 v86, v86
	v_ffbh_u32_e32 v87, v89
	v_sub_u32_e32 v32, 32, v32
	v_min_u32_e32 v87, 32, v87
	v_ldexp_f32 v32, v86, v32
	v_fmamk_f32 v32, v32, 0x30800000, v203
	v_lshlrev_b64 v[88:89], v87, v[88:89]
	v_rsq_f32_e32 v86, v32
	v_min_u32_e32 v32, 1, v88
	v_ffbh_u32_e32 v88, v83
	v_min_u32_e32 v88, 32, v88
	v_lshlrev_b64 v[82:83], v88, v[82:83]
	v_min_u32_e32 v82, 1, v82
	v_or_b32_e32 v32, v89, v32
	v_or_b32_e32 v82, v83, v82
	v_cvt_f32_u32_e32 v32, v32
	v_cvt_f32_u32_e32 v82, v82
	v_sub_u32_e32 v87, 32, v87
	v_sub_u32_e32 v83, 32, v88
	v_ldexp_f32 v32, v32, v87
	v_ldexp_f32 v87, v82, v83
	v_ffbh_u32_e32 v82, v85
	v_min_u32_e32 v88, 32, v82
	v_lshlrev_b64 v[82:83], v88, v[84:85]
	v_min_u32_e32 v82, 1, v82
	v_or_b32_e32 v82, v83, v82
	v_cvt_f32_u32_e32 v83, v82
	v_sub_u32_e32 v84, 32, v88
	v_fmamk_f32 v32, v32, 0x30800000, v203
	v_fmamk_f32 v82, v87, 0x30800000, v203
	v_ldexp_f32 v83, v83, v84
	v_fmamk_f32 v83, v83, 0x30800000, v203
	v_rsq_f32_e32 v82, v82
	v_rsq_f32_e32 v83, v83
	v_rsq_f32_e32 v87, v32
	s_add_u32 s20, s39, s11
	s_addc_u32 s21, s40, s9
	s_lshl_b64 s[18:19], s[18:19], 1
	s_add_u32 s18, s20, s18
	v_mul_u32_u24_e32 v88, s17, v164
	v_mul_i32_i24_e32 v242, s17, v245
	v_lshl_add_u32 v242, v242, 1, v246
	v_ashrrev_i32_e32 v243, 31, v242
	v_pk_mul_f32 v[80:81], v[80:81], v[82:83]
	v_pk_mul_f32 v[78:79], v[78:79], v[86:87]
	s_addc_u32 s19, s21, s19
	v_lshlrev_b32_e32 v32, 1, v88
	v_cvt_pk_bf16_f32 v78, v78, v79
	v_cvt_pk_bf16_f32 v79, v80, v81
	v_lshl_add_u64 v[80:81], s[18:19], 0, v[32:33]
	s_lshl_b64 s[20:21], s[56:57], 1
	v_pk_mul_f32 v[76:77], v[76:77], v[82:83]
	v_pk_mul_f32 v[74:75], v[74:75], v[86:87]
	s_lshl_b32 s22, s17, 4
	s_lshl_b32 s56, s17, 5
	s_mulk_i32 s17, 0x70
	v_cvt_pk_bf16_f32 v74, v74, v75
	v_cvt_pk_bf16_f32 v75, v76, v77
	v_lshl_add_u64 v[76:77], v[80:81], 0, s[56:57]
	s_lshl_b32 s56, s17, 1
	s_add_i32 s17, s22, s17
	v_pk_mul_f32 v[68:69], v[68:69], v[82:83]
	v_pk_mul_f32 v[66:67], v[66:67], v[86:87]
	s_add_i32 s17, s17, s22
	v_lshl_add_u64 v[84:85], v[80:81], 0, s[20:21]
	v_lshlrev_b32_e32 v32, 1, v142
	v_pk_mul_f32 v[72:73], v[72:73], v[82:83]
	v_pk_mul_f32 v[70:71], v[70:71], v[86:87]
	v_cvt_pk_bf16_f32 v66, v66, v67
	v_cvt_pk_bf16_f32 v67, v68, v69
	v_add_lshl_u32 v68, s17, v88, 1
	v_mov_b32_e32 v69, v33
	v_lshl_add_u64 v[84:85], v[84:85], 0, v[32:33]
	v_cvt_pk_bf16_f32 v70, v70, v71
	v_cvt_pk_bf16_f32 v71, v72, v73
	v_lshl_add_u64 v[72:73], v[76:77], 0, s[56:57]
	v_lshl_add_u64 v[68:69], s[18:19], 0, v[68:69]
	ds_bpermute_b32 v78, v244, v78
	ds_bpermute_b32 v79, v244, v79
	ds_bpermute_b32 v74, v244, v74
	ds_bpermute_b32 v75, v244, v75
	ds_bpermute_b32 v70, v244, v70
	ds_bpermute_b32 v71, v244, v71
	ds_bpermute_b32 v66, v244, v66
	ds_bpermute_b32 v67, v244, v67
	v_lshl_add_u64 v[84:85], v[242:243], 0, v[84:85]
	s_waitcnt lgkmcnt(0)
	global_store_dwordx2 v[84:85], v[78:79], off offset:96
	v_lshl_add_u64 v[78:79], v[76:77], 0, s[20:21]
	v_lshl_add_u64 v[72:73], v[72:73], 0, s[20:21]
	v_lshl_add_u64 v[68:69], v[68:69], 0, s[20:21]
	v_lshl_add_u64 v[78:79], v[78:79], 0, v[32:33]
	v_lshl_add_u64 v[72:73], v[72:73], 0, v[32:33]
	v_lshl_add_u64 v[68:69], v[68:69], 0, v[32:33]
	v_lshl_add_u64 v[78:79], v[242:243], 0, v[78:79]
	global_store_dwordx2 v[78:79], v[74:75], off offset:96
	v_lshl_add_u64 v[72:73], v[242:243], 0, v[72:73]
	global_store_dwordx2 v[72:73], v[70:71], off offset:96
	v_lshl_add_u64 v[68:69], v[242:243], 0, v[68:69]
	global_store_dwordx2 v[68:69], v[66:67], off offset:96

; __device__ __forceinline__ float ss_rinv(u64 v) { return __builtin_amdgcn_rsqf((float)v * SS_INV + 1e-6f); }
; __device__ __forceinline__ unsigned cvtpk(float lo, float hi) { f32x2 v = {lo, hi}; bf16x2_t b = __builtin_convertvector(v, bf16x2_t); return __builtin_bit_cast(unsigned, b); }
;     __device__ __forceinline__ void operator()(const f32x4 (&acc)[2][2][4][2], const pg8::Unit& u, int wr, int wc, int fr, int fq) const {
;     ...
;                 const u64x2 s01 = *(const u64x2*)(rowss + row0 + 4 * fq), s23 = *(const u64x2*)(rowss + row0 + 4 * fq + 2);
;                 f32x4 ri; ri[0] = ss_rinv(s01[0]); ri[1] = ss_rinv(s01[1]); ri[2] = ss_rinv(s23[0]); ri[3] = ss_rinv(s23[1]);
;                 int s, p0, L; row_decode(row0, s, p0, L);
;                 const size_t so = seq_off_ch(s); const int LS = seq_LS(s);
; #pragma unroll
;                 for (int bj = 0; bj < 2; ++bj)
; #pragma unroll
;                     for (int n = 0; n < 2; ++n) {
;                         const int col = u.pn * 256 + bj * 128 + wc * 32 + n * 16 + fr;
;                         const int part = col >> 10, ch = col & 1023;
;                         const f32x4 v = acc[ai][bj][m][n] * ri;
;                         u32x2 w; w.x = cvtpk(v[0], v[1]); w.y = cvtpk(v[2], v[3]);
;                         *(u32x2*)(XT + (size_t)part * REGION + so + (size_t)ch * LS + XPAD + p0 + 4 * fq) = w;
;                     }
.LBB0_1085:
	v_ffbh_u32_e32 v32, v71
	v_min_u32_e32 v32, 32, v32
	v_lshlrev_b64 v[70:71], v32, v[70:71]
	v_min_u32_e32 v70, 1, v70
	v_or_b32_e32 v70, v71, v70
	v_cvt_f32_u32_e32 v70, v70
	v_ffbh_u32_e32 v71, v73
	v_sub_u32_e32 v32, 32, v32
	v_min_u32_e32 v71, 32, v71
	v_ldexp_f32 v32, v70, v32
	v_fmamk_f32 v32, v32, 0x30800000, v203
	v_lshlrev_b64 v[72:73], v71, v[72:73]
	v_rsq_f32_e32 v70, v32
	v_min_u32_e32 v32, 1, v72
	v_ffbh_u32_e32 v72, v67
	v_min_u32_e32 v72, 32, v72
	v_lshlrev_b64 v[66:67], v72, v[66:67]
	v_min_u32_e32 v66, 1, v66
	v_or_b32_e32 v32, v73, v32
	v_or_b32_e32 v66, v67, v66
	v_cvt_f32_u32_e32 v32, v32
	v_cvt_f32_u32_e32 v66, v66
	v_sub_u32_e32 v71, 32, v71
	v_sub_u32_e32 v67, 32, v72
	v_ldexp_f32 v32, v32, v71
	v_ldexp_f32 v71, v66, v67
	v_ffbh_u32_e32 v66, v69
	v_min_u32_e32 v72, 32, v66
	v_lshlrev_b64 v[66:67], v72, v[68:69]
	v_min_u32_e32 v66, 1, v66
	v_or_b32_e32 v66, v67, v66
	v_cvt_f32_u32_e32 v67, v66
	v_sub_u32_e32 v68, 32, v72
	v_fmamk_f32 v32, v32, 0x30800000, v203
	v_fmamk_f32 v66, v71, 0x30800000, v203
	v_ldexp_f32 v67, v67, v68
	v_fmamk_f32 v67, v67, 0x30800000, v203
	v_rsq_f32_e32 v66, v66
	v_rsq_f32_e32 v67, v67
	v_rsq_f32_e32 v71, v32
	s_add_u32 s21, s39, s11
	s_addc_u32 s23, s40, s9
	s_lshl_b64 s[18:19], s[18:19], 1
	s_add_u32 s18, s21, s18
	v_mul_u32_u24_e32 v72, s20, v164
	v_mul_i32_i24_e32 v242, s20, v245
	v_lshl_add_u32 v242, v242, 1, v246
	v_ashrrev_i32_e32 v243, 31, v242
	v_pk_mul_f32 v[64:65], v[64:65], v[66:67]
	v_pk_mul_f32 v[62:63], v[62:63], v[70:71]
	s_addc_u32 s19, s23, s19
	v_lshlrev_b32_e32 v32, 1, v72
	v_cvt_pk_bf16_f32 v62, v62, v63
	v_cvt_pk_bf16_f32 v63, v64, v65
	v_lshl_add_u64 v[64:65], s[18:19], 0, v[32:33]
	s_lshl_b64 s[24:25], s[56:57], 1
	v_pk_mul_f32 v[60:61], v[60:61], v[66:67]
	v_pk_mul_f32 v[58:59], v[58:59], v[70:71]
	s_lshl_b32 s21, s20, 4
	s_lshl_b32 s56, s20, 5
	s_mulk_i32 s20, 0x70
	v_cvt_pk_bf16_f32 v58, v58, v59
	v_cvt_pk_bf16_f32 v59, v60, v61
	v_lshl_add_u64 v[60:61], v[64:65], 0, s[56:57]
	s_lshl_b32 s56, s20, 1
	s_add_i32 s20, s21, s20
	v_pk_mul_f32 v[52:53], v[52:53], v[66:67]
	v_pk_mul_f32 v[50:51], v[50:51], v[70:71]
	s_add_i32 s20, s20, s21
	v_lshl_add_u64 v[68:69], v[64:65], 0, s[24:25]
	v_lshlrev_b32_e32 v32, 1, v142
	v_pk_mul_f32 v[56:57], v[56:57], v[66:67]
	v_pk_mul_f32 v[54:55], v[54:55], v[70:71]
	v_cvt_pk_bf16_f32 v50, v50, v51
	v_cvt_pk_bf16_f32 v51, v52, v53
	v_add_lshl_u32 v52, s20, v72, 1
	v_mov_b32_e32 v53, v33
	v_lshl_add_u64 v[68:69], v[68:69], 0, v[32:33]
	v_cvt_pk_bf16_f32 v54, v54, v55
	v_cvt_pk_bf16_f32 v55, v56, v57
	v_lshl_add_u64 v[56:57], v[60:61], 0, s[56:57]
	v_lshl_add_u64 v[52:53], s[18:19], 0, v[52:53]
	ds_bpermute_b32 v62, v244, v62
	ds_bpermute_b32 v63, v244, v63
	ds_bpermute_b32 v58, v244, v58
	ds_bpermute_b32 v59, v244, v59
	ds_bpermute_b32 v54, v244, v54
	ds_bpermute_b32 v55, v244, v55
	ds_bpermute_b32 v50, v244, v50
	ds_bpermute_b32 v51, v244, v51
	v_lshl_add_u64 v[68:69], v[242:243], 0, v[68:69]
	s_waitcnt lgkmcnt(0)
	global_store_dwordx2 v[68:69], v[62:63], off offset:96
	v_lshl_add_u64 v[62:63], v[60:61], 0, s[24:25]
	v_lshl_add_u64 v[56:57], v[56:57], 0, s[24:25]
	v_lshl_add_u64 v[52:53], v[52:53], 0, s[24:25]
	v_lshl_add_u64 v[62:63], v[62:63], 0, v[32:33]
	v_lshl_add_u64 v[56:57], v[56:57], 0, v[32:33]
	v_lshl_add_u64 v[52:53], v[52:53], 0, v[32:33]
	v_lshl_add_u64 v[62:63], v[242:243], 0, v[62:63]
	global_store_dwordx2 v[62:63], v[58:59], off offset:96
	v_lshl_add_u64 v[56:57], v[242:243], 0, v[56:57]
	global_store_dwordx2 v[56:57], v[54:55], off offset:96
	v_lshl_add_u64 v[52:53], v[242:243], 0, v[52:53]
	global_store_dwordx2 v[52:53], v[50:51], off offset:96
	s_add_i32 s18, s16, 0x90
	s_cmp_gt_i32 s18, 0x1813f
	s_cbranch_scc0 .LBB0_1073

; __device__ __forceinline__ float ss_rinv(u64 v) { return __builtin_amdgcn_rsqf((float)v * SS_INV + 1e-6f); }
; __device__ __forceinline__ unsigned cvtpk(float lo, float hi) { f32x2 v = {lo, hi}; bf16x2_t b = __builtin_convertvector(v, bf16x2_t); return __builtin_bit_cast(unsigned, b); }
;     __device__ __forceinline__ void operator()(const f32x4 (&acc)[2][2][4][2], const pg8::Unit& u, int wr, int wc, int fr, int fq) const {
;     ...
;                 const u64x2 s01 = *(const u64x2*)(rowss + row0 + 4 * fq), s23 = *(const u64x2*)(rowss + row0 + 4 * fq + 2);
;                 f32x4 ri; ri[0] = ss_rinv(s01[0]); ri[1] = ss_rinv(s01[1]); ri[2] = ss_rinv(s23[0]); ri[3] = ss_rinv(s23[1]);
;                 int s, p0, L; row_decode(row0, s, p0, L);
;                 const size_t so = seq_off_ch(s); const int LS = seq_LS(s);
; #pragma unroll
;                 for (int bj = 0; bj < 2; ++bj)
; #pragma unroll
;                     for (int n = 0; n < 2; ++n) {
;                         const int col = u.pn * 256 + bj * 128 + wc * 32 + n * 16 + fr;
;                         const int part = col >> 10, ch = col & 1023;
;                         const f32x4 v = acc[ai][bj][m][n] * ri;
;                         u32x2 w; w.x = cvtpk(v[0], v[1]); w.y = cvtpk(v[2], v[3]);
;                         *(u32x2*)(XT + (size_t)part * REGION + so + (size_t)ch * LS + XPAD + p0 + 4 * fq) = w;
;                     }
.LBB0_1099:
	v_ffbh_u32_e32 v32, v55
	v_min_u32_e32 v32, 32, v32
	v_lshlrev_b64 v[54:55], v32, v[54:55]
	v_min_u32_e32 v54, 1, v54
	v_or_b32_e32 v54, v55, v54
	v_cvt_f32_u32_e32 v54, v54
	v_ffbh_u32_e32 v55, v57
	v_sub_u32_e32 v32, 32, v32
	v_min_u32_e32 v55, 32, v55
	v_ldexp_f32 v32, v54, v32
	v_fmamk_f32 v32, v32, 0x30800000, v203
	v_lshlrev_b64 v[56:57], v55, v[56:57]
	v_rsq_f32_e32 v54, v32
	v_min_u32_e32 v32, 1, v56
	v_ffbh_u32_e32 v56, v51
	v_min_u32_e32 v56, 32, v56
	v_lshlrev_b64 v[50:51], v56, v[50:51]
	v_min_u32_e32 v50, 1, v50
	v_or_b32_e32 v32, v57, v32
	v_or_b32_e32 v50, v51, v50
	v_cvt_f32_u32_e32 v32, v32
	v_cvt_f32_u32_e32 v50, v50
	v_sub_u32_e32 v55, 32, v55
	v_sub_u32_e32 v51, 32, v56
	v_ldexp_f32 v32, v32, v55
	v_ldexp_f32 v55, v50, v51
	v_ffbh_u32_e32 v50, v53
	v_min_u32_e32 v56, 32, v50
	v_lshlrev_b64 v[50:51], v56, v[52:53]
	v_min_u32_e32 v50, 1, v50
	v_or_b32_e32 v50, v51, v50
	v_cvt_f32_u32_e32 v51, v50
	v_sub_u32_e32 v52, 32, v56
	v_fmamk_f32 v32, v32, 0x30800000, v203
	v_fmamk_f32 v50, v55, 0x30800000, v203
	v_ldexp_f32 v51, v51, v52
	v_fmamk_f32 v51, v51, 0x30800000, v203
	v_rsq_f32_e32 v50, v50
	v_rsq_f32_e32 v51, v51
	v_rsq_f32_e32 v55, v32
	s_add_u32 s21, s39, s11
	s_addc_u32 s23, s40, s9
	s_lshl_b64 s[18:19], s[18:19], 1
	s_add_u32 s18, s21, s18
	v_mul_u32_u24_e32 v56, s20, v164
	v_mul_i32_i24_e32 v242, s20, v245
	v_lshl_add_u32 v242, v242, 1, v246
	v_ashrrev_i32_e32 v243, 31, v242
	v_pk_mul_f32 v[48:49], v[48:49], v[50:51]
	v_pk_mul_f32 v[46:47], v[46:47], v[54:55]
	s_addc_u32 s19, s23, s19
	v_lshlrev_b32_e32 v32, 1, v56
	v_cvt_pk_bf16_f32 v46, v46, v47
	v_cvt_pk_bf16_f32 v47, v48, v49
	v_lshl_add_u64 v[48:49], s[18:19], 0, v[32:33]
	s_lshl_b64 s[24:25], s[56:57], 1
	v_pk_mul_f32 v[44:45], v[44:45], v[50:51]
	v_pk_mul_f32 v[42:43], v[42:43], v[54:55]
	s_lshl_b32 s21, s20, 4
	s_lshl_b32 s56, s20, 5
	s_mulk_i32 s20, 0x70
	v_cvt_pk_bf16_f32 v42, v42, v43
	v_cvt_pk_bf16_f32 v43, v44, v45
	v_lshl_add_u64 v[44:45], v[48:49], 0, s[56:57]
	s_lshl_b32 s56, s20, 1
	s_add_i32 s20, s21, s20
	v_pk_mul_f32 v[36:37], v[36:37], v[50:51]
	v_pk_mul_f32 v[34:35], v[34:35], v[54:55]
	s_add_i32 s20, s20, s21
	v_lshl_add_u64 v[52:53], v[48:49], 0, s[24:25]
	v_lshlrev_b32_e32 v32, 1, v142
	v_pk_mul_f32 v[40:41], v[40:41], v[50:51]
	v_pk_mul_f32 v[38:39], v[38:39], v[54:55]
	v_cvt_pk_bf16_f32 v34, v34, v35
	v_cvt_pk_bf16_f32 v35, v36, v37
	v_add_lshl_u32 v36, s20, v56, 1
	v_mov_b32_e32 v37, v33
	v_lshl_add_u64 v[52:53], v[52:53], 0, v[32:33]
	v_cvt_pk_bf16_f32 v38, v38, v39
	v_cvt_pk_bf16_f32 v39, v40, v41
	v_lshl_add_u64 v[40:41], v[44:45], 0, s[56:57]
	v_lshl_add_u64 v[36:37], s[18:19], 0, v[36:37]
	ds_bpermute_b32 v46, v244, v46
	ds_bpermute_b32 v47, v244, v47
	ds_bpermute_b32 v42, v244, v42
	ds_bpermute_b32 v43, v244, v43
	ds_bpermute_b32 v38, v244, v38
	ds_bpermute_b32 v39, v244, v39
	ds_bpermute_b32 v34, v244, v34
	ds_bpermute_b32 v35, v244, v35
	v_lshl_add_u64 v[52:53], v[242:243], 0, v[52:53]
	s_waitcnt lgkmcnt(0)
	global_store_dwordx2 v[52:53], v[46:47], off offset:96
	v_lshl_add_u64 v[46:47], v[44:45], 0, s[24:25]
	v_lshl_add_u64 v[40:41], v[40:41], 0, s[24:25]
	v_lshl_add_u64 v[36:37], v[36:37], 0, s[24:25]
	v_lshl_add_u64 v[46:47], v[46:47], 0, v[32:33]
	v_lshl_add_u64 v[40:41], v[40:41], 0, v[32:33]
	v_lshl_add_u64 v[36:37], v[36:37], 0, v[32:33]
	v_lshl_add_u64 v[46:47], v[242:243], 0, v[46:47]
	global_store_dwordx2 v[46:47], v[42:43], off offset:96
	v_lshl_add_u64 v[40:41], v[242:243], 0, v[40:41]
	global_store_dwordx2 v[40:41], v[38:39], off offset:96
	v_lshl_add_u64 v[36:37], v[242:243], 0, v[36:37]
	global_store_dwordx2 v[36:37], v[34:35], off offset:96
	s_add_i32 s18, s16, 0xa0
	s_cmp_gt_i32 s18, 0x1813f
	s_cbranch_scc0 .LBB0_1087

; __device__ __forceinline__ float ss_rinv(u64 v) { return __builtin_amdgcn_rsqf((float)v * SS_INV + 1e-6f); }
; __device__ __forceinline__ unsigned cvtpk(float lo, float hi) { f32x2 v = {lo, hi}; bf16x2_t b = __builtin_convertvector(v, bf16x2_t); return __builtin_bit_cast(unsigned, b); }
;     __device__ __forceinline__ void operator()(const f32x4 (&acc)[2][2][4][2], const pg8::Unit& u, int wr, int wc, int fr, int fq) const {
;     ...
;                 const u64x2 s01 = *(const u64x2*)(rowss + row0 + 4 * fq), s23 = *(const u64x2*)(rowss + row0 + 4 * fq + 2);
;                 f32x4 ri; ri[0] = ss_rinv(s01[0]); ri[1] = ss_rinv(s01[1]); ri[2] = ss_rinv(s23[0]); ri[3] = ss_rinv(s23[1]);
;                 int s, p0, L; row_decode(row0, s, p0, L);
;                 const size_t so = seq_off_ch(s); const int LS = seq_LS(s);
; #pragma unroll
;                 for (int bj = 0; bj < 2; ++bj)
; #pragma unroll
;                     for (int n = 0; n < 2; ++n) {
;                         const int col = u.pn * 256 + bj * 128 + wc * 32 + n * 16 + fr;
;                         const int part = col >> 10, ch = col & 1023;
;                         const f32x4 v = acc[ai][bj][m][n] * ri;
;                         u32x2 w; w.x = cvtpk(v[0], v[1]); w.y = cvtpk(v[2], v[3]);
;                         *(u32x2*)(XT + (size_t)part * REGION + so + (size_t)ch * LS + XPAD + p0 + 4 * fq) = w;
;                     }
.LBB0_1113:
	v_ffbh_u32_e32 v32, v39
	v_min_u32_e32 v32, 32, v32
	v_lshlrev_b64 v[38:39], v32, v[38:39]
	v_min_u32_e32 v38, 1, v38
	v_or_b32_e32 v38, v39, v38
	v_cvt_f32_u32_e32 v38, v38
	v_ffbh_u32_e32 v39, v41
	v_sub_u32_e32 v32, 32, v32
	v_min_u32_e32 v39, 32, v39
	v_ldexp_f32 v32, v38, v32
	v_fmamk_f32 v32, v32, 0x30800000, v203
	v_lshlrev_b64 v[40:41], v39, v[40:41]
	v_rsq_f32_e32 v38, v32
	v_min_u32_e32 v32, 1, v40
	v_ffbh_u32_e32 v40, v35
	v_min_u32_e32 v40, 32, v40
	v_lshlrev_b64 v[34:35], v40, v[34:35]
	v_min_u32_e32 v34, 1, v34
	v_or_b32_e32 v32, v41, v32
	v_or_b32_e32 v34, v35, v34
	v_cvt_f32_u32_e32 v32, v32
	v_cvt_f32_u32_e32 v34, v34
	v_sub_u32_e32 v39, 32, v39
	v_sub_u32_e32 v35, 32, v40
	v_ldexp_f32 v32, v32, v39
	v_ldexp_f32 v39, v34, v35
	v_ffbh_u32_e32 v34, v37
	v_min_u32_e32 v40, 32, v34
	v_lshlrev_b64 v[34:35], v40, v[36:37]
	v_min_u32_e32 v34, 1, v34
	v_or_b32_e32 v34, v35, v34
	v_cvt_f32_u32_e32 v35, v34
	v_sub_u32_e32 v36, 32, v40
	v_fmamk_f32 v32, v32, 0x30800000, v203
	v_fmamk_f32 v34, v39, 0x30800000, v203
	v_ldexp_f32 v35, v35, v36
	v_fmamk_f32 v35, v35, 0x30800000, v203
	v_rsq_f32_e32 v34, v34
	v_rsq_f32_e32 v35, v35
	v_rsq_f32_e32 v39, v32
	s_add_u32 s21, s39, s11
	s_addc_u32 s23, s40, s9
	s_lshl_b64 s[18:19], s[18:19], 1
	s_add_u32 s18, s21, s18
	v_mul_u32_u24_e32 v40, s20, v164
	v_mul_i32_i24_e32 v242, s20, v245
	v_lshl_add_u32 v242, v242, 1, v246
	v_ashrrev_i32_e32 v243, 31, v242
	v_pk_mul_f32 v[30:31], v[30:31], v[34:35]
	v_pk_mul_f32 v[28:29], v[28:29], v[38:39]
	s_addc_u32 s19, s23, s19
	v_lshlrev_b32_e32 v32, 1, v40
	v_cvt_pk_bf16_f32 v28, v28, v29
	v_cvt_pk_bf16_f32 v29, v30, v31
	v_lshl_add_u64 v[30:31], s[18:19], 0, v[32:33]
	s_lshl_b64 s[24:25], s[56:57], 1
	v_pk_mul_f32 v[26:27], v[26:27], v[34:35]
	v_pk_mul_f32 v[24:25], v[24:25], v[38:39]
	s_lshl_b32 s21, s20, 4
	s_lshl_b32 s56, s20, 5
	s_mulk_i32 s20, 0x70
	v_cvt_pk_bf16_f32 v24, v24, v25
	v_cvt_pk_bf16_f32 v25, v26, v27
	v_lshl_add_u64 v[26:27], v[30:31], 0, s[56:57]
	s_lshl_b32 s56, s20, 1
	s_add_i32 s20, s21, s20
	v_pk_mul_f32 v[18:19], v[18:19], v[34:35]
	v_pk_mul_f32 v[16:17], v[16:17], v[38:39]
	s_add_i32 s20, s20, s21
	v_lshl_add_u64 v[36:37], v[30:31], 0, s[24:25]
	v_lshlrev_b32_e32 v32, 1, v142
	v_pk_mul_f32 v[22:23], v[22:23], v[34:35]
	v_pk_mul_f32 v[20:21], v[20:21], v[38:39]
	v_cvt_pk_bf16_f32 v16, v16, v17
	v_cvt_pk_bf16_f32 v17, v18, v19
	v_add_lshl_u32 v18, s20, v40, 1
	v_mov_b32_e32 v19, v33
	v_lshl_add_u64 v[36:37], v[36:37], 0, v[32:33]
	v_cvt_pk_bf16_f32 v20, v20, v21
	v_cvt_pk_bf16_f32 v21, v22, v23
	v_lshl_add_u64 v[22:23], v[26:27], 0, s[56:57]
	v_lshl_add_u64 v[18:19], s[18:19], 0, v[18:19]
	ds_bpermute_b32 v28, v244, v28
	ds_bpermute_b32 v29, v244, v29
	ds_bpermute_b32 v24, v244, v24
	ds_bpermute_b32 v25, v244, v25
	ds_bpermute_b32 v20, v244, v20
	ds_bpermute_b32 v21, v244, v21
	ds_bpermute_b32 v16, v244, v16
	ds_bpermute_b32 v17, v244, v17
	v_lshl_add_u64 v[36:37], v[242:243], 0, v[36:37]
	s_waitcnt lgkmcnt(0)
	global_store_dwordx2 v[36:37], v[28:29], off offset:96
	v_lshl_add_u64 v[28:29], v[26:27], 0, s[24:25]
	v_lshl_add_u64 v[22:23], v[22:23], 0, s[24:25]
	v_lshl_add_u64 v[18:19], v[18:19], 0, s[24:25]
	v_lshl_add_u64 v[28:29], v[28:29], 0, v[32:33]
	v_lshl_add_u64 v[22:23], v[22:23], 0, v[32:33]
	v_lshl_add_u64 v[18:19], v[18:19], 0, v[32:33]
	v_lshl_add_u64 v[28:29], v[242:243], 0, v[28:29]
	global_store_dwordx2 v[28:29], v[24:25], off offset:96
	v_lshl_add_u64 v[22:23], v[242:243], 0, v[22:23]
	global_store_dwordx2 v[22:23], v[20:21], off offset:96
	v_lshl_add_u64 v[18:19], v[242:243], 0, v[18:19]
	global_store_dwordx2 v[18:19], v[16:17], off offset:96
	s_add_i32 s18, s16, 0xb0
	s_cmp_gt_i32 s18, 0x1813f
	s_cbranch_scc0 .LBB0_1101

; __device__ __forceinline__ float ss_rinv(u64 v) { return __builtin_amdgcn_rsqf((float)v * SS_INV + 1e-6f); }
; __device__ __forceinline__ unsigned cvtpk(float lo, float hi) { f32x2 v = {lo, hi}; bf16x2_t b = __builtin_convertvector(v, bf16x2_t); return __builtin_bit_cast(unsigned, b); }
;     __device__ __forceinline__ void operator()(const f32x4 (&acc)[2][2][4][2], const pg8::Unit& u, int wr, int wc, int fr, int fq) const {
;     ...
;                 const u64x2 s01 = *(const u64x2*)(rowss + row0 + 4 * fq), s23 = *(const u64x2*)(rowss + row0 + 4 * fq + 2);
;                 f32x4 ri; ri[0] = ss_rinv(s01[0]); ri[1] = ss_rinv(s01[1]); ri[2] = ss_rinv(s23[0]); ri[3] = ss_rinv(s23[1]);
;                 int s, p0, L; row_decode(row0, s, p0, L);
;                 const size_t so = seq_off_ch(s); const int LS = seq_LS(s);
; #pragma unroll
;                 for (int bj = 0; bj < 2; ++bj)
; #pragma unroll
;                     for (int n = 0; n < 2; ++n) {
;                         const int col = u.pn * 256 + bj * 128 + wc * 32 + n * 16 + fr;
;                         const int part = col >> 10, ch = col & 1023;
;                         const f32x4 v = acc[ai][bj][m][n] * ri;
;                         u32x2 w; w.x = cvtpk(v[0], v[1]); w.y = cvtpk(v[2], v[3]);
;                         *(u32x2*)(XT + (size_t)part * REGION + so + (size_t)ch * LS + XPAD + p0 + 4 * fq) = w;
;                     }
.LBB0_1119:
	v_ffbh_u32_e32 v24, v21
	v_min_u32_e32 v24, 32, v24
	v_lshlrev_b64 v[20:21], v24, v[20:21]
	v_min_u32_e32 v20, 1, v20
	v_or_b32_e32 v20, v21, v20
	v_ffbh_u32_e32 v21, v23
	v_min_u32_e32 v21, 32, v21
	v_lshlrev_b64 v[22:23], v21, v[22:23]
	v_min_u32_e32 v22, 1, v22
	v_or_b32_e32 v22, v23, v22
	v_ffbh_u32_e32 v23, v17
	v_min_u32_e32 v23, 32, v23
	v_lshlrev_b64 v[16:17], v23, v[16:17]
	v_cvt_f32_u32_e32 v22, v22
	v_min_u32_e32 v16, 1, v16
	v_or_b32_e32 v16, v17, v16
	v_cvt_f32_u32_e32 v16, v16
	v_sub_u32_e32 v21, 32, v21
	v_ldexp_f32 v17, v22, v21
	v_fmamk_f32 v21, v17, 0x30800000, v203
	v_sub_u32_e32 v17, 32, v23
	v_ldexp_f32 v22, v16, v17
	v_ffbh_u32_e32 v16, v19
	v_min_u32_e32 v23, 32, v16
	v_lshlrev_b64 v[16:17], v23, v[18:19]
	v_min_u32_e32 v16, 1, v16
	v_or_b32_e32 v16, v17, v16
	v_cvt_f32_u32_e32 v20, v20
	v_cvt_f32_u32_e32 v17, v16
	v_sub_u32_e32 v24, 32, v24
	v_sub_u32_e32 v18, 32, v23
	v_ldexp_f32 v20, v20, v24
	v_ldexp_f32 v17, v17, v18
	v_fmamk_f32 v20, v20, 0x30800000, v203
	v_fmamk_f32 v16, v22, 0x30800000, v203
	v_fmamk_f32 v17, v17, 0x30800000, v203
	v_rsq_f32_e32 v20, v20
	v_rsq_f32_e32 v16, v16
	v_rsq_f32_e32 v17, v17
	v_rsq_f32_e32 v21, v21
	s_add_u32 s11, s39, s11
	s_addc_u32 s9, s40, s9
	s_lshl_b64 s[16:17], s[16:17], 1
	s_add_u32 s16, s11, s16
	v_mul_u32_u24_e32 v22, s18, v164
	v_mul_i32_i24_e32 v242, s18, v245
	v_lshl_add_u32 v242, v242, 1, v246
	v_ashrrev_i32_e32 v243, 31, v242
	v_pk_mul_f32 v[14:15], v[14:15], v[16:17]
	v_pk_mul_f32 v[12:13], v[12:13], v[20:21]
	s_addc_u32 s17, s9, s17
	v_lshlrev_b32_e32 v32, 1, v22
	v_cvt_pk_bf16_f32 v12, v12, v13
	v_cvt_pk_bf16_f32 v13, v14, v15
	v_lshl_add_u64 v[14:15], s[16:17], 0, v[32:33]
	s_lshl_b64 s[20:21], s[56:57], 1
	v_pk_mul_f32 v[10:11], v[10:11], v[16:17]
	v_pk_mul_f32 v[8:9], v[8:9], v[20:21]
	s_lshl_b32 s9, s18, 4
	s_lshl_b32 s56, s18, 5
	s_mul_i32 s11, s18, 0x70
	v_cvt_pk_bf16_f32 v8, v8, v9
	v_cvt_pk_bf16_f32 v9, v10, v11
	v_lshl_add_u64 v[10:11], v[14:15], 0, s[56:57]
	s_lshl_b32 s56, s11, 1
	s_add_i32 s11, s9, s11
	v_pk_mul_f32 v[2:3], v[2:3], v[16:17]
	v_pk_mul_f32 v[0:1], v[0:1], v[20:21]
	s_add_i32 s11, s11, s9
	v_lshl_add_u64 v[18:19], v[14:15], 0, s[20:21]
	v_lshlrev_b32_e32 v32, 1, v142
	v_pk_mul_f32 v[6:7], v[6:7], v[16:17]
	v_pk_mul_f32 v[4:5], v[4:5], v[20:21]
	v_cvt_pk_bf16_f32 v0, v0, v1
	v_cvt_pk_bf16_f32 v1, v2, v3
	v_add_lshl_u32 v2, s11, v22, 1
	v_mov_b32_e32 v3, v33
	v_lshl_add_u64 v[18:19], v[18:19], 0, v[32:33]
	v_cvt_pk_bf16_f32 v4, v4, v5
	v_cvt_pk_bf16_f32 v5, v6, v7
	v_lshl_add_u64 v[6:7], v[10:11], 0, s[56:57]
	v_lshl_add_u64 v[2:3], s[16:17], 0, v[2:3]
	ds_bpermute_b32 v12, v244, v12
	ds_bpermute_b32 v13, v244, v13
	ds_bpermute_b32 v8, v244, v8
	ds_bpermute_b32 v9, v244, v9
	ds_bpermute_b32 v4, v244, v4
	ds_bpermute_b32 v5, v244, v5
	ds_bpermute_b32 v0, v244, v0
	ds_bpermute_b32 v1, v244, v1
	v_lshl_add_u64 v[18:19], v[242:243], 0, v[18:19]
	s_waitcnt lgkmcnt(0)
	global_store_dwordx2 v[18:19], v[12:13], off offset:96
	v_lshl_add_u64 v[12:13], v[10:11], 0, s[20:21]
	v_lshl_add_u64 v[6:7], v[6:7], 0, s[20:21]
	v_lshl_add_u64 v[2:3], v[2:3], 0, s[20:21]
	v_lshl_add_u64 v[12:13], v[12:13], 0, v[32:33]
	v_lshl_add_u64 v[6:7], v[6:7], 0, v[32:33]
	v_lshl_add_u64 v[2:3], v[2:3], 0, v[32:33]
	v_lshl_add_u64 v[12:13], v[242:243], 0, v[12:13]
	global_store_dwordx2 v[12:13], v[8:9], off offset:96
	v_lshl_add_u64 v[6:7], v[242:243], 0, v[6:7]
	global_store_dwordx2 v[6:7], v[4:5], off offset:96
	v_lshl_add_u64 v[2:3], v[242:243], 0, v[2:3]
	global_store_dwordx2 v[2:3], v[0:1], off offset:96
	s_andn2_b64 vcc, exec, s[2:3]
	s_mov_b64 s[2:3], -1
	s_cbranch_vccnz .LBB0_1000
